# speedup vs baseline: 1.0017x; 1.0017x over previous
.LBB0_711:
	v_lshl_add_u32 v144, s28, 8, v133
	s_lshl_b32 s12, s8, 8
	s_ashr_i32 s13, s12, 31
	v_ashrrev_i32_e32 v145, 31, v144
	v_mov_b32_e32 v143, s13
	v_or_b32_e32 v142, s12, v132
	v_lshlrev_b64 v[152:153], 10, v[144:145]
	v_lshl_add_u64 v[156:157], v[152:153], 0, v[142:143]
	v_lshl_add_u64 v[158:159], v[156:157], 2, s[52:53]
	global_load_dwordx4 v[164:167], v[158:159], off
	global_load_dwordx4 v[168:171], v[158:159], off offset:64
	global_load_dwordx4 v[172:175], v[158:159], off offset:512
	global_load_dwordx4 v[176:179], v[158:159], off offset:576
	v_add_co_u32_e32 v184, vcc, 0x10000, v158
	s_nop 1
	v_addc_co_u32_e32 v185, vcc, 0, v159, vcc
	global_load_dwordx4 v[180:183], v[184:185], off
	global_load_dwordx4 v[188:191], v[184:185], off offset:64
	global_load_dwordx4 v[192:195], v[184:185], off offset:512
	global_load_dwordx4 v[196:199], v[184:185], off offset:576
	v_add_co_u32_e32 v184, vcc, 0x20000, v158
	s_nop 1
	v_addc_co_u32_e32 v185, vcc, 0, v159, vcc
	global_load_dwordx4 v[200:203], v[184:185], off
	global_load_dwordx4 v[204:207], v[184:185], off offset:64
	global_load_dwordx4 v[208:211], v[184:185], off offset:512
	global_load_dwordx4 v[212:215], v[184:185], off offset:576
	v_add_co_u32_e32 v184, vcc, 0x30000, v158
	s_nop 1
	v_addc_co_u32_e32 v185, vcc, 0, v159, vcc
	global_load_dwordx4 v[216:219], v[184:185], off
	global_load_dwordx4 v[220:223], v[184:185], off offset:64
	global_load_dwordx4 v[224:227], v[184:185], off offset:512
	global_load_dwordx4 v[228:231], v[184:185], off offset:576
	s_waitcnt vmcnt(0)
	v_mbcnt_lo_u32_b32 v252, -1, 0
	v_mbcnt_hi_u32_b32 v252, -1, v252
	v_and_b32_e32 v252, 16, v252
	v_lshrrev_b32_e32 v253, 1, v252
	v_add_u32_e32 v252, v252, v253
	v_mov_b32_e32 v253, 0
	v_lshlrev_b64 v[156:157], 1, v[156:157]
	v_lshl_add_u64 v[160:161], s[62:63], 0, v[156:157]
	v_xor_b32_e32 v151, 32, v150
	s_lshl_b32 s28, s8, 2
	s_ashr_i32 s29, s28, 31
	v_mov_b64_e32 v[152:153], v[164:165]
	v_mov_b64_e32 v[154:155], v[166:167]
	v_pk_add_f32 v[154:155], v[126:127], v[154:155]
	v_pk_add_f32 v[152:153], v[124:125], v[152:153]
	s_nop 0
	v_cvt_pk_bf16_f32 v244, v152, v153
	v_cvt_pk_bf16_f32 v245, v154, v155
	v_lshl_add_u64 v[242:243], v[160:161], 0, v[252:253]
	v_or_b32_e32 v160, 32, v156
	v_mov_b32_e32 v161, v157
	v_lshl_add_u64 v[160:161], s[62:63], 0, v[160:161]
	v_mul_f32_e32 v153, v153, v153
	v_mul_f32_e32 v155, v155, v155
	v_fmac_f32_e32 v153, v152, v152
	v_fmac_f32_e32 v155, v154, v154
	v_add_f32_e32 v152, v153, v155
	v_mov_b64_e32 v[124:125], v[168:169]
	v_mov_b64_e32 v[126:127], v[170:171]
	v_pk_add_f32 v[126:127], v[122:123], v[126:127]
	v_pk_add_f32 v[124:125], v[120:121], v[124:125]
	s_nop 0
	v_cvt_pk_bf16_f32 v246, v124, v125
	v_cvt_pk_bf16_f32 v247, v126, v127
	s_nop 1
	v_permlane16_swap_b32_e32 v244, v246
	v_permlane16_swap_b32_e32 v245, v247
	global_store_dwordx4 v[242:243], v[244:247], off sc0 sc1
	v_or_b32_e32 v160, 0x100, v156
	v_mov_b32_e32 v161, v157
	v_lshl_add_u64 v[160:161], s[62:63], 0, v[160:161]
	v_mul_f32_e32 v125, v125, v125
	v_mul_f32_e32 v127, v127, v127
	v_fmac_f32_e32 v125, v124, v124
	v_fmac_f32_e32 v127, v126, v126
	v_add_f32_e32 v124, v125, v127
	v_add_f32_e32 v124, v152, v124
	v_or_b32_e32 v156, 0x120, v156
	v_mov_b64_e32 v[120:121], v[172:173]
	v_mov_b64_e32 v[122:123], v[174:175]
	v_pk_add_f32 v[122:123], v[118:119], v[122:123]
	v_pk_add_f32 v[162:163], v[116:117], v[120:121]
	s_nop 0
	v_cvt_pk_bf16_f32 v248, v162, v163
	v_cvt_pk_bf16_f32 v249, v122, v123
	v_lshl_add_u64 v[240:241], v[160:161], 0, v[252:253]
	v_and_b32_e32 v117, 64, v150
	v_mul_f32_e32 v125, v163, v163
	v_mul_f32_e32 v123, v123, v123
	v_xor_b32_e32 v116, 16, v150
	v_add_u32_e32 v117, 64, v117
	v_fmac_f32_e32 v125, v162, v162
	v_fmac_f32_e32 v123, v122, v122
	v_cmp_lt_i32_e32 vcc, v116, v117
	v_add_f32_e32 v122, v125, v123
	v_add_f32_e32 v122, v124, v122
	v_cndmask_b32_e32 v116, v150, v116, vcc
	v_lshlrev_b32_e32 v116, 2, v116
	v_cmp_lt_i32_e32 vcc, v151, v117
	v_mov_b64_e32 v[118:119], v[176:177]
	v_mov_b64_e32 v[120:121], v[178:179]
	v_pk_add_f32 v[120:121], v[114:115], v[120:121]
	v_pk_add_f32 v[112:113], v[112:113], v[118:119]
	v_mul_f32_e32 v115, v121, v121
	v_mul_f32_e32 v114, v113, v113
	v_fmac_f32_e32 v114, v112, v112
	v_fmac_f32_e32 v115, v120, v120
	v_add_f32_e32 v114, v114, v115
	v_add_f32_e32 v114, v122, v114
	ds_bpermute_b32 v115, v116, v114
	v_cndmask_b32_e32 v117, v150, v151, vcc
	v_cvt_pk_bf16_f32 v250, v112, v113
	v_cvt_pk_bf16_f32 v251, v120, v121
	v_lshl_add_u64 v[120:121], s[62:63], 0, v[156:157]
	s_waitcnt lgkmcnt(0)
	v_add_f32_e32 v112, v114, v115
	v_lshlrev_b32_e32 v114, 2, v117
	ds_bpermute_b32 v113, v114, v112
	s_nop 1
	v_permlane16_swap_b32_e32 v248, v250
	v_permlane16_swap_b32_e32 v249, v251
	global_store_dwordx4 v[240:241], v[248:251], off sc0 sc1
	s_and_saveexec_b64 s[30:31], s[4:5]
	s_cbranch_execz .LBB0_713
	v_lshlrev_b64 v[118:119], 6, v[144:145]
	v_lshl_add_u64 v[118:119], s[60:61], 0, v[118:119]
	v_lshl_add_u64 v[118:119], s[28:29], 2, v[118:119]
	s_lshl_b32 s8, s47, 2
	v_lshl_add_u64 v[118:119], v[118:119], 0, s[8:9]
	s_waitcnt lgkmcnt(0)
	v_add_f32_e32 v112, v112, v113
	global_store_dword v[118:119], v112, off
.LBB0_713:
	s_or_b64 exec, exec, s[30:31]
	v_or_b32_e32 v112, 16, v144
	s_waitcnt lgkmcnt(0)
	v_ashrrev_i32_e32 v113, 31, v112
	v_lshlrev_b64 v[118:119], 10, v[112:113]
	v_lshl_add_u64 v[122:123], v[118:119], 0, v[142:143]
	v_lshl_add_u64 v[124:125], v[122:123], 2, s[52:53]
	v_lshlrev_b64 v[122:123], 1, v[122:123]
	v_lshl_add_u64 v[126:127], s[62:63], 0, v[122:123]
	v_mov_b64_e32 v[118:119], v[180:181]
	v_mov_b64_e32 v[120:121], v[182:183]
	v_pk_add_f32 v[120:121], v[110:111], v[120:121]
	v_pk_add_f32 v[118:119], v[108:109], v[118:119]
	v_mul_f32_e32 v117, v121, v121
	v_cvt_pk_bf16_f32 v244, v118, v119
	v_cvt_pk_bf16_f32 v245, v120, v121
	v_lshl_add_u64 v[242:243], v[126:127], 0, v[252:253]
	v_or_b32_e32 v126, 32, v122
	v_mov_b32_e32 v127, v123
	v_lshl_add_u64 v[126:127], s[62:63], 0, v[126:127]
	v_mul_f32_e32 v115, v119, v119
	v_fmac_f32_e32 v115, v118, v118
	v_fmac_f32_e32 v117, v120, v120
	v_add_f32_e32 v115, v115, v117
	v_mov_b64_e32 v[108:109], v[188:189]
	v_mov_b64_e32 v[110:111], v[190:191]
	v_pk_add_f32 v[110:111], v[106:107], v[110:111]
	v_pk_add_f32 v[108:109], v[104:105], v[108:109]
	s_nop 0
	v_cvt_pk_bf16_f32 v246, v108, v109
	v_cvt_pk_bf16_f32 v247, v110, v111
	s_nop 1
	v_permlane16_swap_b32_e32 v244, v246
	v_permlane16_swap_b32_e32 v245, v247
	global_store_dwordx4 v[242:243], v[244:247], off sc0 sc1
	v_or_b32_e32 v126, 0x100, v122
	v_mov_b32_e32 v127, v123
	v_lshl_add_u64 v[126:127], s[62:63], 0, v[126:127]
	v_mul_f32_e32 v109, v109, v109
	v_mul_f32_e32 v111, v111, v111
	v_fmac_f32_e32 v109, v108, v108
	v_fmac_f32_e32 v111, v110, v110
	v_add_f32_e32 v108, v109, v111
	v_add_f32_e32 v108, v115, v108
	v_or_b32_e32 v122, 0x120, v122
	v_mov_b64_e32 v[104:105], v[192:193]
	v_mov_b64_e32 v[106:107], v[194:195]
	v_pk_add_f32 v[106:107], v[102:103], v[106:107]
	v_pk_add_f32 v[104:105], v[100:101], v[104:105]
	s_nop 0
	v_cvt_pk_bf16_f32 v248, v104, v105
	v_cvt_pk_bf16_f32 v249, v106, v107
	v_lshl_add_u64 v[240:241], v[126:127], 0, v[252:253]
	v_mul_f32_e32 v105, v105, v105
	v_mul_f32_e32 v107, v107, v107
	v_fmac_f32_e32 v105, v104, v104
	v_fmac_f32_e32 v107, v106, v106
	v_add_f32_e32 v104, v105, v107
	v_add_f32_e32 v104, v108, v104
	v_mov_b64_e32 v[100:101], v[196:197]
	v_mov_b64_e32 v[102:103], v[198:199]
	v_pk_add_f32 v[98:99], v[98:99], v[102:103]
	v_pk_add_f32 v[96:97], v[96:97], v[100:101]
	v_mul_f32_e32 v101, v99, v99
	v_mul_f32_e32 v100, v97, v97
	v_fmac_f32_e32 v100, v96, v96
	v_fmac_f32_e32 v101, v98, v98
	v_add_f32_e32 v100, v100, v101
	v_add_f32_e32 v101, v104, v100
	ds_bpermute_b32 v102, v116, v101
	v_cvt_pk_bf16_f32 v250, v96, v97
	s_waitcnt lgkmcnt(0)
	v_add_f32_e32 v96, v101, v102
	ds_bpermute_b32 v97, v114, v96
	v_cvt_pk_bf16_f32 v251, v98, v99
	v_lshl_add_u64 v[98:99], s[62:63], 0, v[122:123]
	s_nop 1
	v_permlane16_swap_b32_e32 v248, v250
	v_permlane16_swap_b32_e32 v249, v251
	global_store_dwordx4 v[240:241], v[248:251], off sc0 sc1
	s_and_saveexec_b64 s[30:31], s[4:5]
	s_cbranch_execz .LBB0_715
	v_lshlrev_b64 v[98:99], 6, v[112:113]
	v_lshl_add_u64 v[98:99], s[60:61], 0, v[98:99]
	v_lshl_add_u64 v[98:99], s[28:29], 2, v[98:99]
	s_lshl_b32 s8, s47, 2
	v_lshl_add_u64 v[98:99], v[98:99], 0, s[8:9]
	s_waitcnt lgkmcnt(0)
	v_add_f32_e32 v96, v96, v97
	global_store_dword v[98:99], v96, off
.LBB0_715:
	s_or_b64 exec, exec, s[30:31]
	v_or_b32_e32 v96, 32, v144
	s_waitcnt lgkmcnt(0)
	v_ashrrev_i32_e32 v97, 31, v96
	v_lshlrev_b64 v[98:99], 10, v[96:97]
	v_lshl_add_u64 v[102:103], v[98:99], 0, v[142:143]
	v_lshl_add_u64 v[104:105], v[102:103], 2, s[52:53]
	v_lshlrev_b64 v[102:103], 1, v[102:103]
	v_lshl_add_u64 v[106:107], s[62:63], 0, v[102:103]
	v_mov_b64_e32 v[98:99], v[200:201]
	v_mov_b64_e32 v[100:101], v[202:203]
	v_pk_add_f32 v[100:101], v[94:95], v[100:101]
	v_pk_add_f32 v[98:99], v[92:93], v[98:99]
	s_nop 0
	v_cvt_pk_bf16_f32 v244, v98, v99
	v_cvt_pk_bf16_f32 v245, v100, v101
	v_lshl_add_u64 v[242:243], v[106:107], 0, v[252:253]
	v_or_b32_e32 v106, 32, v102
	v_mov_b32_e32 v107, v103
	v_lshl_add_u64 v[106:107], s[62:63], 0, v[106:107]
	v_mul_f32_e32 v99, v99, v99
	v_mul_f32_e32 v101, v101, v101
	v_fmac_f32_e32 v99, v98, v98
	v_fmac_f32_e32 v101, v100, v100
	v_add_f32_e32 v98, v99, v101
	v_mov_b64_e32 v[92:93], v[204:205]
	v_mov_b64_e32 v[94:95], v[206:207]
	v_pk_add_f32 v[94:95], v[90:91], v[94:95]
	v_pk_add_f32 v[92:93], v[88:89], v[92:93]
	s_nop 0
	v_cvt_pk_bf16_f32 v246, v92, v93
	v_cvt_pk_bf16_f32 v247, v94, v95
	s_nop 1
	v_permlane16_swap_b32_e32 v244, v246
	v_permlane16_swap_b32_e32 v245, v247
	global_store_dwordx4 v[242:243], v[244:247], off sc0 sc1
	v_or_b32_e32 v106, 0x100, v102
	v_mov_b32_e32 v107, v103
	v_lshl_add_u64 v[106:107], s[62:63], 0, v[106:107]
	v_mul_f32_e32 v93, v93, v93
	v_mul_f32_e32 v95, v95, v95
	v_fmac_f32_e32 v93, v92, v92
	v_fmac_f32_e32 v95, v94, v94
	v_add_f32_e32 v92, v93, v95
	v_add_f32_e32 v92, v98, v92
	v_or_b32_e32 v102, 0x120, v102
	v_mov_b64_e32 v[88:89], v[208:209]
	v_mov_b64_e32 v[90:91], v[210:211]
	v_pk_add_f32 v[90:91], v[86:87], v[90:91]
	v_pk_add_f32 v[88:89], v[84:85], v[88:89]
	s_nop 0
	v_cvt_pk_bf16_f32 v248, v88, v89
	v_cvt_pk_bf16_f32 v249, v90, v91
	v_lshl_add_u64 v[240:241], v[106:107], 0, v[252:253]
	v_mul_f32_e32 v89, v89, v89
	v_mul_f32_e32 v91, v91, v91
	v_fmac_f32_e32 v89, v88, v88
	v_fmac_f32_e32 v91, v90, v90
	v_add_f32_e32 v88, v89, v91
	v_add_f32_e32 v88, v92, v88
	v_mov_b64_e32 v[84:85], v[212:213]
	v_mov_b64_e32 v[86:87], v[214:215]
	v_pk_add_f32 v[82:83], v[82:83], v[86:87]
	v_pk_add_f32 v[80:81], v[80:81], v[84:85]
	v_mul_f32_e32 v85, v83, v83
	v_mul_f32_e32 v84, v81, v81
	v_fmac_f32_e32 v84, v80, v80
	v_fmac_f32_e32 v85, v82, v82
	v_add_f32_e32 v84, v84, v85
	v_add_f32_e32 v85, v88, v84
	ds_bpermute_b32 v86, v116, v85
	v_cvt_pk_bf16_f32 v250, v80, v81
	s_waitcnt lgkmcnt(0)
	v_add_f32_e32 v80, v85, v86
	ds_bpermute_b32 v81, v114, v80
	v_cvt_pk_bf16_f32 v251, v82, v83
	v_lshl_add_u64 v[82:83], s[62:63], 0, v[102:103]
	s_nop 1
	v_permlane16_swap_b32_e32 v248, v250
	v_permlane16_swap_b32_e32 v249, v251
	global_store_dwordx4 v[240:241], v[248:251], off sc0 sc1
	s_and_saveexec_b64 s[30:31], s[4:5]
	s_cbranch_execz .LBB0_717
	v_lshlrev_b64 v[82:83], 6, v[96:97]
	v_lshl_add_u64 v[82:83], s[60:61], 0, v[82:83]
	v_lshl_add_u64 v[82:83], s[28:29], 2, v[82:83]
	s_lshl_b32 s8, s47, 2
	v_lshl_add_u64 v[82:83], v[82:83], 0, s[8:9]
	s_waitcnt lgkmcnt(0)
	v_add_f32_e32 v80, v80, v81
	global_store_dword v[82:83], v80, off
.LBB0_717:
	s_or_b64 exec, exec, s[30:31]
	v_or_b32_e32 v80, 48, v144
	s_waitcnt lgkmcnt(0)
	v_ashrrev_i32_e32 v81, 31, v80
	v_lshlrev_b64 v[82:83], 10, v[80:81]
	v_lshl_add_u64 v[86:87], v[82:83], 0, v[142:143]
	v_lshl_add_u64 v[88:89], v[86:87], 2, s[52:53]
	v_lshlrev_b64 v[86:87], 1, v[86:87]
	v_lshl_add_u64 v[90:91], s[62:63], 0, v[86:87]
	v_mov_b64_e32 v[82:83], v[216:217]
	v_mov_b64_e32 v[84:85], v[218:219]
	v_pk_add_f32 v[84:85], v[78:79], v[84:85]
	v_pk_add_f32 v[82:83], v[76:77], v[82:83]
	s_nop 0
	v_cvt_pk_bf16_f32 v244, v82, v83
	v_cvt_pk_bf16_f32 v245, v84, v85
	v_lshl_add_u64 v[242:243], v[90:91], 0, v[252:253]
	v_or_b32_e32 v90, 32, v86
	v_mov_b32_e32 v91, v87
	v_lshl_add_u64 v[90:91], s[62:63], 0, v[90:91]
	v_mul_f32_e32 v83, v83, v83
	v_mul_f32_e32 v85, v85, v85
	v_fmac_f32_e32 v83, v82, v82
	v_fmac_f32_e32 v85, v84, v84
	v_add_f32_e32 v82, v83, v85
	v_mov_b64_e32 v[76:77], v[220:221]
	v_mov_b64_e32 v[78:79], v[222:223]
	v_pk_add_f32 v[78:79], v[74:75], v[78:79]
	v_pk_add_f32 v[76:77], v[72:73], v[76:77]
	s_nop 0
	v_cvt_pk_bf16_f32 v246, v76, v77
	v_cvt_pk_bf16_f32 v247, v78, v79
	s_nop 1
	v_permlane16_swap_b32_e32 v244, v246
	v_permlane16_swap_b32_e32 v245, v247
	global_store_dwordx4 v[242:243], v[244:247], off sc0 sc1
	v_or_b32_e32 v90, 0x100, v86
	v_mov_b32_e32 v91, v87
	v_lshl_add_u64 v[90:91], s[62:63], 0, v[90:91]
	v_mul_f32_e32 v77, v77, v77
	v_mul_f32_e32 v79, v79, v79
	v_fmac_f32_e32 v77, v76, v76
	v_fmac_f32_e32 v79, v78, v78
	v_add_f32_e32 v76, v77, v79
	v_add_f32_e32 v76, v82, v76
	v_or_b32_e32 v86, 0x120, v86
	v_mov_b64_e32 v[72:73], v[224:225]
	v_mov_b64_e32 v[74:75], v[226:227]
	v_pk_add_f32 v[74:75], v[70:71], v[74:75]
	v_pk_add_f32 v[72:73], v[68:69], v[72:73]
	s_nop 0
	v_cvt_pk_bf16_f32 v248, v72, v73
	v_cvt_pk_bf16_f32 v249, v74, v75
	v_lshl_add_u64 v[240:241], v[90:91], 0, v[252:253]
	v_mul_f32_e32 v73, v73, v73
	v_mul_f32_e32 v75, v75, v75
	v_fmac_f32_e32 v73, v72, v72
	v_fmac_f32_e32 v75, v74, v74
	v_add_f32_e32 v72, v73, v75
	v_add_f32_e32 v72, v76, v72
	v_mov_b64_e32 v[68:69], v[228:229]
	v_mov_b64_e32 v[70:71], v[230:231]
	v_pk_add_f32 v[66:67], v[66:67], v[70:71]
	v_pk_add_f32 v[64:65], v[64:65], v[68:69]
	v_mul_f32_e32 v69, v67, v67
	v_mul_f32_e32 v68, v65, v65
	v_fmac_f32_e32 v68, v64, v64
	v_fmac_f32_e32 v69, v66, v66
	v_add_f32_e32 v68, v68, v69
	v_add_f32_e32 v69, v72, v68
	ds_bpermute_b32 v70, v116, v69
	v_cvt_pk_bf16_f32 v250, v64, v65
	s_waitcnt lgkmcnt(0)
	v_add_f32_e32 v64, v69, v70
	ds_bpermute_b32 v65, v114, v64
	v_cvt_pk_bf16_f32 v251, v66, v67
	v_lshl_add_u64 v[66:67], s[62:63], 0, v[86:87]
	s_nop 1
	v_permlane16_swap_b32_e32 v248, v250
	v_permlane16_swap_b32_e32 v249, v251
	global_store_dwordx4 v[240:241], v[248:251], off sc0 sc1
	s_and_saveexec_b64 s[30:31], s[4:5]
	s_cbranch_execz .LBB0_719
	v_lshlrev_b64 v[66:67], 6, v[80:81]
	v_lshl_add_u64 v[66:67], s[60:61], 0, v[66:67]
	v_lshl_add_u64 v[66:67], s[28:29], 2, v[66:67]
	s_lshl_b32 s8, s47, 2
	v_lshl_add_u64 v[66:67], v[66:67], 0, s[8:9]
	s_waitcnt lgkmcnt(0)
	v_add_f32_e32 v64, v64, v65
	global_store_dword v[66:67], v64, off
.LBB0_719:
	s_or_b64 exec, exec, s[30:31]
	v_add_u32_e32 v64, 0x80, v144
	s_waitcnt lgkmcnt(0)
	v_ashrrev_i32_e32 v65, 31, v64
	v_lshlrev_b64 v[66:67], 10, v[64:65]
	v_lshl_add_u64 v[70:71], v[66:67], 0, v[142:143]
	v_lshl_add_u64 v[72:73], v[70:71], 2, s[52:53]
	global_load_dwordx4 v[164:167], v[72:73], off
	global_load_dwordx4 v[168:171], v[72:73], off offset:64
	global_load_dwordx4 v[172:175], v[72:73], off offset:512
	global_load_dwordx4 v[176:179], v[72:73], off offset:576
	v_add_co_u32_e32 v184, vcc, 0x10000, v72
	s_nop 1
	v_addc_co_u32_e32 v185, vcc, 0, v73, vcc
	global_load_dwordx4 v[180:183], v[184:185], off
	global_load_dwordx4 v[188:191], v[184:185], off offset:64
	global_load_dwordx4 v[192:195], v[184:185], off offset:512
	global_load_dwordx4 v[196:199], v[184:185], off offset:576
	v_add_co_u32_e32 v184, vcc, 0x20000, v72
	s_nop 1
	v_addc_co_u32_e32 v185, vcc, 0, v73, vcc
	global_load_dwordx4 v[200:203], v[184:185], off
	global_load_dwordx4 v[204:207], v[184:185], off offset:64
	global_load_dwordx4 v[208:211], v[184:185], off offset:512
	global_load_dwordx4 v[212:215], v[184:185], off offset:576
	v_add_co_u32_e32 v184, vcc, 0x30000, v72
	s_nop 1
	v_addc_co_u32_e32 v185, vcc, 0, v73, vcc
	global_load_dwordx4 v[216:219], v[184:185], off
	global_load_dwordx4 v[220:223], v[184:185], off offset:64
	global_load_dwordx4 v[224:227], v[184:185], off offset:512
	global_load_dwordx4 v[228:231], v[184:185], off offset:576
	s_waitcnt vmcnt(0)
	v_lshlrev_b64 v[70:71], 1, v[70:71]
	v_lshl_add_u64 v[74:75], s[62:63], 0, v[70:71]
	v_mov_b64_e32 v[66:67], v[164:165]
	v_mov_b64_e32 v[68:69], v[166:167]
	v_pk_add_f32 v[68:69], v[62:63], v[68:69]
	v_pk_add_f32 v[66:67], v[60:61], v[66:67]
	s_nop 0
	v_cvt_pk_bf16_f32 v244, v66, v67
	v_cvt_pk_bf16_f32 v245, v68, v69
	v_lshl_add_u64 v[242:243], v[74:75], 0, v[252:253]
	v_or_b32_e32 v74, 32, v70
	v_mov_b32_e32 v75, v71
	v_lshl_add_u64 v[74:75], s[62:63], 0, v[74:75]
	v_mul_f32_e32 v67, v67, v67
	v_mul_f32_e32 v69, v69, v69
	v_fmac_f32_e32 v67, v66, v66
	v_fmac_f32_e32 v69, v68, v68
	v_add_f32_e32 v66, v67, v69
	v_mov_b64_e32 v[60:61], v[168:169]
	v_mov_b64_e32 v[62:63], v[170:171]
	v_pk_add_f32 v[62:63], v[58:59], v[62:63]
	v_pk_add_f32 v[60:61], v[56:57], v[60:61]
	s_nop 0
	v_cvt_pk_bf16_f32 v246, v60, v61
	v_cvt_pk_bf16_f32 v247, v62, v63
	s_nop 1
	v_permlane16_swap_b32_e32 v244, v246
	v_permlane16_swap_b32_e32 v245, v247
	global_store_dwordx4 v[242:243], v[244:247], off sc0 sc1
	v_or_b32_e32 v74, 0x100, v70
	v_mov_b32_e32 v75, v71
	v_lshl_add_u64 v[74:75], s[62:63], 0, v[74:75]
	v_mul_f32_e32 v61, v61, v61
	v_mul_f32_e32 v63, v63, v63
	v_fmac_f32_e32 v61, v60, v60
	v_fmac_f32_e32 v63, v62, v62
	v_add_f32_e32 v60, v61, v63
	v_add_f32_e32 v60, v66, v60
	v_or_b32_e32 v70, 0x120, v70
	v_mov_b64_e32 v[56:57], v[172:173]
	v_mov_b64_e32 v[58:59], v[174:175]
	v_pk_add_f32 v[58:59], v[54:55], v[58:59]
	v_pk_add_f32 v[56:57], v[52:53], v[56:57]
	s_nop 0
	v_cvt_pk_bf16_f32 v248, v56, v57
	v_cvt_pk_bf16_f32 v249, v58, v59
	v_lshl_add_u64 v[240:241], v[74:75], 0, v[252:253]
	v_mul_f32_e32 v57, v57, v57
	v_mul_f32_e32 v59, v59, v59
	v_fmac_f32_e32 v57, v56, v56
	v_fmac_f32_e32 v59, v58, v58
	v_add_f32_e32 v56, v57, v59
	v_add_f32_e32 v56, v60, v56
	v_mov_b64_e32 v[52:53], v[176:177]
	v_mov_b64_e32 v[54:55], v[178:179]
	v_pk_add_f32 v[50:51], v[50:51], v[54:55]
	v_pk_add_f32 v[48:49], v[48:49], v[52:53]
	v_mul_f32_e32 v53, v51, v51
	v_mul_f32_e32 v52, v49, v49
	v_fmac_f32_e32 v52, v48, v48
	v_fmac_f32_e32 v53, v50, v50
	v_add_f32_e32 v52, v52, v53
	v_add_f32_e32 v53, v56, v52
	ds_bpermute_b32 v54, v116, v53
	v_cvt_pk_bf16_f32 v250, v48, v49
	s_waitcnt lgkmcnt(0)
	v_add_f32_e32 v48, v53, v54
	ds_bpermute_b32 v49, v114, v48
	v_cvt_pk_bf16_f32 v251, v50, v51
	v_lshl_add_u64 v[50:51], s[62:63], 0, v[70:71]
	s_nop 1
	v_permlane16_swap_b32_e32 v248, v250
	v_permlane16_swap_b32_e32 v249, v251
	global_store_dwordx4 v[240:241], v[248:251], off sc0 sc1
	s_and_saveexec_b64 s[30:31], s[4:5]
	s_cbranch_execz .LBB0_721
	v_lshlrev_b64 v[50:51], 6, v[64:65]
	v_lshl_add_u64 v[50:51], s[60:61], 0, v[50:51]
	v_lshl_add_u64 v[50:51], s[28:29], 2, v[50:51]
	s_lshl_b32 s8, s47, 2
	v_lshl_add_u64 v[50:51], v[50:51], 0, s[8:9]
	s_waitcnt lgkmcnt(0)
	v_add_f32_e32 v48, v48, v49
	global_store_dword v[50:51], v48, off
.LBB0_721:
	s_or_b64 exec, exec, s[30:31]
	v_add_u32_e32 v48, 0x90, v144
	s_waitcnt lgkmcnt(0)
	v_ashrrev_i32_e32 v49, 31, v48
	v_lshlrev_b64 v[50:51], 10, v[48:49]
	v_lshl_add_u64 v[54:55], v[50:51], 0, v[142:143]
	v_lshl_add_u64 v[56:57], v[54:55], 2, s[52:53]
	v_lshlrev_b64 v[54:55], 1, v[54:55]
	v_lshl_add_u64 v[58:59], s[62:63], 0, v[54:55]
	v_mov_b64_e32 v[50:51], v[180:181]
	v_mov_b64_e32 v[52:53], v[182:183]
	v_pk_add_f32 v[52:53], v[46:47], v[52:53]
	v_pk_add_f32 v[50:51], v[44:45], v[50:51]
	s_nop 0
	v_cvt_pk_bf16_f32 v244, v50, v51
	v_cvt_pk_bf16_f32 v245, v52, v53
	v_lshl_add_u64 v[242:243], v[58:59], 0, v[252:253]
	v_or_b32_e32 v58, 32, v54
	v_mov_b32_e32 v59, v55
	v_lshl_add_u64 v[58:59], s[62:63], 0, v[58:59]
	v_mul_f32_e32 v51, v51, v51
	v_mul_f32_e32 v53, v53, v53
	v_fmac_f32_e32 v51, v50, v50
	v_fmac_f32_e32 v53, v52, v52
	v_add_f32_e32 v50, v51, v53
	v_mov_b64_e32 v[44:45], v[188:189]
	v_mov_b64_e32 v[46:47], v[190:191]
	v_pk_add_f32 v[46:47], v[42:43], v[46:47]
	v_pk_add_f32 v[44:45], v[40:41], v[44:45]
	s_nop 0
	v_cvt_pk_bf16_f32 v246, v44, v45
	v_cvt_pk_bf16_f32 v247, v46, v47
	s_nop 1
	v_permlane16_swap_b32_e32 v244, v246
	v_permlane16_swap_b32_e32 v245, v247
	global_store_dwordx4 v[242:243], v[244:247], off sc0 sc1
	v_or_b32_e32 v58, 0x100, v54
	v_mov_b32_e32 v59, v55
	v_lshl_add_u64 v[58:59], s[62:63], 0, v[58:59]
	v_mul_f32_e32 v45, v45, v45
	v_mul_f32_e32 v47, v47, v47
	v_fmac_f32_e32 v45, v44, v44
	v_fmac_f32_e32 v47, v46, v46
	v_add_f32_e32 v44, v45, v47
	v_add_f32_e32 v44, v50, v44
	v_or_b32_e32 v54, 0x120, v54
	v_mov_b64_e32 v[40:41], v[192:193]
	v_mov_b64_e32 v[42:43], v[194:195]
	v_pk_add_f32 v[42:43], v[38:39], v[42:43]
	v_pk_add_f32 v[40:41], v[36:37], v[40:41]
	s_nop 0
	v_cvt_pk_bf16_f32 v248, v40, v41
	v_cvt_pk_bf16_f32 v249, v42, v43
	v_lshl_add_u64 v[240:241], v[58:59], 0, v[252:253]
	v_mul_f32_e32 v41, v41, v41
	v_mul_f32_e32 v43, v43, v43
	v_fmac_f32_e32 v41, v40, v40
	v_fmac_f32_e32 v43, v42, v42
	v_add_f32_e32 v40, v41, v43
	v_add_f32_e32 v40, v44, v40
	v_mov_b64_e32 v[36:37], v[196:197]
	v_mov_b64_e32 v[38:39], v[198:199]
	v_pk_add_f32 v[34:35], v[34:35], v[38:39]
	v_pk_add_f32 v[32:33], v[32:33], v[36:37]
	v_mul_f32_e32 v37, v35, v35
	v_mul_f32_e32 v36, v33, v33
	v_fmac_f32_e32 v36, v32, v32
	v_fmac_f32_e32 v37, v34, v34
	v_add_f32_e32 v36, v36, v37
	v_add_f32_e32 v37, v40, v36
	ds_bpermute_b32 v38, v116, v37
	v_cvt_pk_bf16_f32 v250, v32, v33
	s_waitcnt lgkmcnt(0)
	v_add_f32_e32 v32, v37, v38
	ds_bpermute_b32 v33, v114, v32
	v_cvt_pk_bf16_f32 v251, v34, v35
	v_lshl_add_u64 v[34:35], s[62:63], 0, v[54:55]
	s_nop 1
	v_permlane16_swap_b32_e32 v248, v250
	v_permlane16_swap_b32_e32 v249, v251
	global_store_dwordx4 v[240:241], v[248:251], off sc0 sc1
	s_and_saveexec_b64 s[30:31], s[4:5]
	s_cbranch_execz .LBB0_723
	v_lshlrev_b64 v[34:35], 6, v[48:49]
	v_lshl_add_u64 v[34:35], s[60:61], 0, v[34:35]
	v_lshl_add_u64 v[34:35], s[28:29], 2, v[34:35]
	s_lshl_b32 s8, s47, 2
	v_lshl_add_u64 v[34:35], v[34:35], 0, s[8:9]
	s_waitcnt lgkmcnt(0)
	v_add_f32_e32 v32, v32, v33
	global_store_dword v[34:35], v32, off
.LBB0_723:
	s_or_b64 exec, exec, s[30:31]
	v_add_u32_e32 v32, 0xa0, v144
	s_waitcnt lgkmcnt(0)
	v_ashrrev_i32_e32 v33, 31, v32
	v_lshlrev_b64 v[34:35], 10, v[32:33]
	v_lshl_add_u64 v[38:39], v[34:35], 0, v[142:143]
	v_lshl_add_u64 v[40:41], v[38:39], 2, s[52:53]
	v_lshlrev_b64 v[38:39], 1, v[38:39]
	v_lshl_add_u64 v[42:43], s[62:63], 0, v[38:39]
	v_mov_b64_e32 v[34:35], v[200:201]
	v_mov_b64_e32 v[36:37], v[202:203]
	v_pk_add_f32 v[36:37], v[30:31], v[36:37]
	v_pk_add_f32 v[34:35], v[28:29], v[34:35]
	s_nop 0
	v_cvt_pk_bf16_f32 v244, v34, v35
	v_cvt_pk_bf16_f32 v245, v36, v37
	v_lshl_add_u64 v[242:243], v[42:43], 0, v[252:253]
	v_or_b32_e32 v42, 32, v38
	v_mov_b32_e32 v43, v39
	v_lshl_add_u64 v[42:43], s[62:63], 0, v[42:43]
	v_mul_f32_e32 v35, v35, v35
	v_mul_f32_e32 v37, v37, v37
	v_fmac_f32_e32 v35, v34, v34
	v_fmac_f32_e32 v37, v36, v36
	v_add_f32_e32 v34, v35, v37
	v_mov_b64_e32 v[28:29], v[204:205]
	v_mov_b64_e32 v[30:31], v[206:207]
	v_pk_add_f32 v[30:31], v[26:27], v[30:31]
	v_pk_add_f32 v[28:29], v[24:25], v[28:29]
	s_nop 0
	v_cvt_pk_bf16_f32 v246, v28, v29
	v_cvt_pk_bf16_f32 v247, v30, v31
	s_nop 1
	v_permlane16_swap_b32_e32 v244, v246
	v_permlane16_swap_b32_e32 v245, v247
	global_store_dwordx4 v[242:243], v[244:247], off sc0 sc1
	v_or_b32_e32 v42, 0x100, v38
	v_mov_b32_e32 v43, v39
	v_lshl_add_u64 v[42:43], s[62:63], 0, v[42:43]
	v_mul_f32_e32 v29, v29, v29
	v_mul_f32_e32 v31, v31, v31
	v_fmac_f32_e32 v29, v28, v28
	v_fmac_f32_e32 v31, v30, v30
	v_add_f32_e32 v28, v29, v31
	v_add_f32_e32 v28, v34, v28
	v_or_b32_e32 v38, 0x120, v38
	v_mov_b64_e32 v[24:25], v[208:209]
	v_mov_b64_e32 v[26:27], v[210:211]
	v_pk_add_f32 v[26:27], v[22:23], v[26:27]
	v_pk_add_f32 v[24:25], v[20:21], v[24:25]
	s_nop 0
	v_cvt_pk_bf16_f32 v248, v24, v25
	v_cvt_pk_bf16_f32 v249, v26, v27
	v_lshl_add_u64 v[240:241], v[42:43], 0, v[252:253]
	v_mul_f32_e32 v25, v25, v25
	v_mul_f32_e32 v27, v27, v27
	v_fmac_f32_e32 v25, v24, v24
	v_fmac_f32_e32 v27, v26, v26
	v_add_f32_e32 v24, v25, v27
	v_add_f32_e32 v24, v28, v24
	v_mov_b64_e32 v[20:21], v[212:213]
	v_mov_b64_e32 v[22:23], v[214:215]
	v_pk_add_f32 v[18:19], v[18:19], v[22:23]
	v_pk_add_f32 v[16:17], v[16:17], v[20:21]
	v_mul_f32_e32 v21, v19, v19
	v_mul_f32_e32 v20, v17, v17
	v_fmac_f32_e32 v20, v16, v16
	v_fmac_f32_e32 v21, v18, v18
	v_add_f32_e32 v20, v20, v21
	v_add_f32_e32 v21, v24, v20
	ds_bpermute_b32 v22, v116, v21
	v_cvt_pk_bf16_f32 v250, v16, v17
	s_waitcnt lgkmcnt(0)
	v_add_f32_e32 v16, v21, v22
	ds_bpermute_b32 v17, v114, v16
	v_cvt_pk_bf16_f32 v251, v18, v19
	v_lshl_add_u64 v[18:19], s[62:63], 0, v[38:39]
	s_nop 1
	v_permlane16_swap_b32_e32 v248, v250
	v_permlane16_swap_b32_e32 v249, v251
	global_store_dwordx4 v[240:241], v[248:251], off sc0 sc1
	s_and_saveexec_b64 s[30:31], s[4:5]
	s_cbranch_execz .LBB0_725
	v_lshlrev_b64 v[18:19], 6, v[32:33]
	v_lshl_add_u64 v[18:19], s[60:61], 0, v[18:19]
	v_lshl_add_u64 v[18:19], s[28:29], 2, v[18:19]
	s_lshl_b32 s8, s47, 2
	v_lshl_add_u64 v[18:19], v[18:19], 0, s[8:9]
	s_waitcnt lgkmcnt(0)
	v_add_f32_e32 v16, v16, v17
	global_store_dword v[18:19], v16, off
.LBB0_725:
	s_or_b64 exec, exec, s[30:31]
	v_add_u32_e32 v16, 0xb0, v144
	s_waitcnt lgkmcnt(0)
	v_ashrrev_i32_e32 v17, 31, v16
	v_lshlrev_b64 v[18:19], 10, v[16:17]
	v_lshl_add_u64 v[22:23], v[18:19], 0, v[142:143]
	v_lshl_add_u64 v[24:25], v[22:23], 2, s[52:53]
	v_lshlrev_b64 v[22:23], 1, v[22:23]
	v_lshl_add_u64 v[26:27], s[62:63], 0, v[22:23]
	v_mov_b64_e32 v[18:19], v[216:217]
	v_mov_b64_e32 v[20:21], v[218:219]
	v_pk_add_f32 v[20:21], v[14:15], v[20:21]
	v_pk_add_f32 v[18:19], v[12:13], v[18:19]
	s_nop 0
	v_cvt_pk_bf16_f32 v244, v18, v19
	v_cvt_pk_bf16_f32 v245, v20, v21
	v_lshl_add_u64 v[242:243], v[26:27], 0, v[252:253]
	v_or_b32_e32 v26, 32, v22
	v_mov_b32_e32 v27, v23
	v_lshl_add_u64 v[26:27], s[62:63], 0, v[26:27]
	v_mul_f32_e32 v19, v19, v19
	v_mul_f32_e32 v21, v21, v21
	v_fmac_f32_e32 v19, v18, v18
	v_fmac_f32_e32 v21, v20, v20
	v_add_f32_e32 v18, v19, v21
	v_mov_b64_e32 v[12:13], v[220:221]
	v_mov_b64_e32 v[14:15], v[222:223]
	v_pk_add_f32 v[14:15], v[10:11], v[14:15]
	v_pk_add_f32 v[12:13], v[8:9], v[12:13]
	s_nop 0
	v_cvt_pk_bf16_f32 v246, v12, v13
	v_cvt_pk_bf16_f32 v247, v14, v15
	s_nop 1
	v_permlane16_swap_b32_e32 v244, v246
	v_permlane16_swap_b32_e32 v245, v247
	global_store_dwordx4 v[242:243], v[244:247], off sc0 sc1
	v_or_b32_e32 v26, 0x100, v22
	v_mov_b32_e32 v27, v23
	v_lshl_add_u64 v[26:27], s[62:63], 0, v[26:27]
	v_mul_f32_e32 v13, v13, v13
	v_mul_f32_e32 v15, v15, v15
	v_fmac_f32_e32 v13, v12, v12
	v_fmac_f32_e32 v15, v14, v14
	v_add_f32_e32 v12, v13, v15
	v_add_f32_e32 v12, v18, v12
	v_or_b32_e32 v22, 0x120, v22
	v_mov_b64_e32 v[8:9], v[224:225]
	v_mov_b64_e32 v[10:11], v[226:227]
	v_pk_add_f32 v[10:11], v[6:7], v[10:11]
	v_pk_add_f32 v[8:9], v[4:5], v[8:9]
	s_nop 0
	v_cvt_pk_bf16_f32 v248, v8, v9
	v_cvt_pk_bf16_f32 v249, v10, v11
	v_lshl_add_u64 v[240:241], v[26:27], 0, v[252:253]
	v_mul_f32_e32 v9, v9, v9
	v_mul_f32_e32 v11, v11, v11
	v_fmac_f32_e32 v9, v8, v8
	v_fmac_f32_e32 v11, v10, v10
	v_add_f32_e32 v8, v9, v11
	v_add_f32_e32 v8, v12, v8
	v_mov_b64_e32 v[4:5], v[228:229]
	v_mov_b64_e32 v[6:7], v[230:231]
	v_pk_add_f32 v[2:3], v[2:3], v[6:7]
	v_pk_add_f32 v[0:1], v[0:1], v[4:5]
	v_mul_f32_e32 v5, v3, v3
	v_mul_f32_e32 v4, v1, v1
	v_fmac_f32_e32 v4, v0, v0
	v_fmac_f32_e32 v5, v2, v2
	v_add_f32_e32 v4, v4, v5
	v_add_f32_e32 v5, v8, v4
	ds_bpermute_b32 v6, v116, v5
	v_cvt_pk_bf16_f32 v250, v0, v1
	s_waitcnt lgkmcnt(0)
	v_add_f32_e32 v0, v5, v6
	ds_bpermute_b32 v1, v114, v0
	v_cvt_pk_bf16_f32 v251, v2, v3
	v_lshl_add_u64 v[2:3], s[62:63], 0, v[22:23]
	s_nop 1
	v_permlane16_swap_b32_e32 v248, v250
	v_permlane16_swap_b32_e32 v249, v251
	global_store_dwordx4 v[240:241], v[248:251], off sc0 sc1
	s_and_saveexec_b64 s[30:31], s[4:5]
	s_cbranch_execz .LBB0_727
	v_lshlrev_b64 v[2:3], 6, v[16:17]
	v_lshl_add_u64 v[2:3], s[60:61], 0, v[2:3]
	v_lshl_add_u64 v[2:3], s[28:29], 2, v[2:3]
	s_lshl_b32 s8, s47, 2
	v_lshl_add_u64 v[2:3], v[2:3], 0, s[8:9]
	s_waitcnt lgkmcnt(0)
	v_add_f32_e32 v0, v0, v1
	global_store_dword v[2:3], v0, off
